# scan: y-chain of step1 interleaved with dot-chain of step2 (independent serial chains overlap); on top of attention+GEMM edits
# speedup vs baseline: 1.0263x; 1.0024x over previous
; __device__ __forceinline__ float red8(float x) { x += dppf<0xB1>(x); x += dppf<0x4E>(x); x += dppf<0x141>(x); return x; }
; __device__ __forceinline__ void rwkv_scan_phase(const Params& p, unsigned char* smem) {
;     ...
;         auto step = [&](const Ops& o, const int i) {
;           const int tt = z ? 31 - i : i;
;           f2 t = p01 * F2LO(o.a0);
;           t = p23 * F2HI(o.a0) + t; t = p45 * F2LO(o.a1) + t; t = p67 * F2HI(o.a1) + t;
;           float sa = red8(t.x + t.y);
;           const f2 sa2 = {sa, sa}, vv2 = {o.v, o.v};
;           p01 = p01 * F2LO(o.w0) + (vv2 * F2LO(o.k0) + sa2 * F2LO(o.b0));
;           p23 = p23 * F2HI(o.w0) + (vv2 * F2HI(o.k0) + sa2 * F2HI(o.b0));
;           p45 = p45 * F2LO(o.w1) + (vv2 * F2LO(o.k1) + sa2 * F2LO(o.b1));
;           p67 = p67 * F2HI(o.w1) + (vv2 * F2HI(o.k1) + sa2 * F2HI(o.b1));
;           f2 u = p01 * F2LO(o.r0);
;           u = p23 * F2HI(o.r0) + u; u = p45 * F2LO(o.r1) + u; u = p67 * F2HI(o.r1) + u;
;           const float y = red8(u.x + u.y);
;           if (cg == 0) sY[tt * 64 + srow] = y;
;         };
;         Ops oa, ob;
;         ld(oa, 0);
; #pragma unroll 1
;         for (int i = 0; i < 32; i += 2) {
;           ld(ob, i + 1);
;           step(oa, i);
;           if (i + 2 < 32) ld(oa, i + 2);
;           step(ob, i + 1);
;         }
.LBB0_1208:
	s_waitcnt lgkmcnt(10)
	v_pk_mul_f32 v[206:207], v[58:59], v[170:171]
	s_and_b64 s[44:45], s[36:37], exec
	v_pk_fma_f32 v[206:207], v[56:57], v[168:169], v[206:207]
	s_cselect_b32 s44, s46, s54
	s_waitcnt lgkmcnt(9)
	v_pk_fma_f32 v[206:207], v[60:61], v[172:173], v[206:207]
	s_lshl_b32 s44, s44, 6
	v_pk_fma_f32 v[206:207], v[62:63], v[174:175], v[206:207]
	s_add_i32 s44, s44, 64
	v_add_f32_e32 v149, v206, v207
	v_or_b32_e32 v96, s44, v177
	v_lshlrev_b32_e32 v128, 2, v96
	v_add_f32_dpp v149, v149, v149 quad_perm:[1,0,3,2] row_mask:0xf bank_mask:0xf bound_ctrl:1
	ds_read_b128 v[124:127], v128 offset:24592
	ds_read_b128 v[96:99], v128 offset:8208
	ds_read_b128 v[116:119], v128 offset:16384
	ds_read_b128 v[132:135], v128 offset:24576
	ds_read_b128 v[100:103], v128 offset:16400
	ds_read_b128 v[112:115], v128 offset:32784
	ds_read_b128 v[104:107], v128
	ds_read_b128 v[120:123], v128 offset:8192
	ds_read_b128 v[108:111], v128 offset:16
	v_add_f32_dpp v149, v149, v149 quad_perm:[2,3,0,1] row_mask:0xf bank_mask:0xf bound_ctrl:1
	v_add_lshl_u32 v147, s44, v165, 2
	ds_read_b128 v[128:131], v128 offset:32768
	ds_read_b32 v178, v147 offset:40960
	v_add_f32_dpp v206, v149, v149 row_half_mirror row_mask:0xf bank_mask:0xf bound_ctrl:1
	s_waitcnt lgkmcnt(14)
	v_pk_mul_f32 v[208:209], v[80:81], v[206:207] op_sel_hi:[1,0]
	s_waitcnt lgkmcnt(11)
	v_pk_fma_f32 v[208:209], v[176:177], v[72:73], v[208:209] op_sel_hi:[0,1,1]
	v_pk_fma_f32 v[168:169], v[64:65], v[168:169], v[208:209]
	v_pk_mul_f32 v[208:209], v[82:83], v[206:207] op_sel_hi:[1,0]
	s_nop 0
	v_pk_fma_f32 v[208:209], v[176:177], v[74:75], v[208:209] op_sel_hi:[0,1,1]
	v_pk_fma_f32 v[170:171], v[66:67], v[170:171], v[208:209]
	v_pk_mul_f32 v[208:209], v[84:85], v[206:207] op_sel_hi:[1,0]
	v_pk_mul_f32 v[206:207], v[86:87], v[206:207] op_sel_hi:[1,0]
	v_pk_fma_f32 v[208:209], v[176:177], v[76:77], v[208:209] op_sel_hi:[0,1,1]
	v_pk_fma_f32 v[206:207], v[176:177], v[78:79], v[206:207] op_sel_hi:[0,1,1]
	v_pk_fma_f32 v[174:175], v[70:71], v[174:175], v[206:207]
	v_pk_mul_f32 v[206:207], v[90:91], v[170:171]
	v_pk_fma_f32 v[172:173], v[68:69], v[172:173], v[208:209]
	s_waitcnt lgkmcnt(7)
	v_pk_mul_f32 v[134:135], v[134:135], v[170:171]
	v_pk_fma_f32 v[206:207], v[88:89], v[168:169], v[206:207]
	v_pk_fma_f32 v[132:133], v[132:133], v[168:169], v[134:135]
	v_pk_fma_f32 v[206:207], v[92:93], v[172:173], v[206:207]
	v_pk_fma_f32 v[124:125], v[124:125], v[172:173], v[132:133]
	v_pk_fma_f32 v[206:207], v[94:95], v[174:175], v[206:207]
	v_pk_fma_f32 v[124:125], v[126:127], v[174:175], v[124:125]
	v_add_f32_e32 v149, v206, v207
	v_add_f32_e32 v124, v124, v125
	s_add_i32 s47, s54, 2
	s_and_b64 s[72:73], s[36:37], exec
	s_cselect_b32 s47, s46, s47
	v_lshl_add_u32 v211, s47, 8, v180
	v_add_f32_dpp v149, v149, v149 quad_perm:[1,0,3,2] row_mask:0xf bank_mask:0xf bound_ctrl:1
	v_add_f32_dpp v124, v124, v124 quad_perm:[1,0,3,2] row_mask:0xf bank_mask:0xf bound_ctrl:1
	s_nop 0
	v_add_f32_dpp v149, v149, v149 quad_perm:[2,3,0,1] row_mask:0xf bank_mask:0xf bound_ctrl:1
	v_add_f32_dpp v124, v124, v124 quad_perm:[2,3,0,1] row_mask:0xf bank_mask:0xf bound_ctrl:1
	s_nop 0
	v_mov_b32_dpp v185, v149 row_half_mirror row_mask:0xf bank_mask:0xf bound_ctrl:1
	v_add_f32_dpp v124, v124, v124 row_half_mirror row_mask:0xf bank_mask:0xf bound_ctrl:1
	s_and_saveexec_b64 s[100:101], s[42:43]
	s_cbranch_execz .Lscan_c1_skip
	v_add_f32_e32 v149, v149, v185
	ds_write_b32 v211, v149 offset:49152
.Lscan_c1_skip:
	s_or_b64 exec, exec, s[100:101]
	s_waitcnt lgkmcnt(1)
	v_pk_mul_f32 v[126:127], v[128:129], v[124:125] op_sel_hi:[1,0]
	v_pk_mul_f32 v[112:113], v[112:113], v[124:125] op_sel_hi:[1,0]
	s_waitcnt lgkmcnt(0)
	s_add_i32 s72, s46, 2
	s_cmp_gt_u32 s46, 29
	s_cselect_b64 s[44:45], -1, 0
	s_and_b64 vcc, exec, s[44:45]
	s_cbranch_vccnz .LBB0_1212
	s_and_b64 s[46:47], s[36:37], exec
	s_cselect_b32 s46, s72, s54
	s_lshl_b32 s46, s46, 8
	v_lshl_or_b32 v92, v177, 2, s46
	ds_read_b128 v[56:59], v92 offset:24576
	ds_read_b128 v[60:63], v92 offset:24592
	ds_read_b128 v[64:67], v92 offset:8192
	ds_read_b128 v[68:71], v92 offset:8208
	ds_read_b128 v[72:75], v92 offset:16384
	ds_read_b128 v[76:79], v92 offset:16400
	ds_read_b128 v[80:83], v92 offset:32768
	ds_read_b128 v[84:87], v92 offset:32784
	ds_read_b128 v[88:91], v92
	ds_read_b128 v[92:95], v92 offset:16
	v_add_u32_e32 v149, s46, v180
	ds_read_b32 v176, v149 offset:40960
.LBB0_1212:
	v_pk_fma_f32 v[116:117], v[116:117], v[178:179], v[126:127] op_sel_hi:[1,0,1]
	v_pk_fma_f32 v[100:101], v[100:101], v[178:179], v[112:113] op_sel_hi:[1,0,1]
	v_pk_fma_f32 v[168:169], v[120:121], v[168:169], v[116:117]
	v_pk_mul_f32 v[116:117], v[130:131], v[124:125] op_sel_hi:[1,0]
	v_pk_fma_f32 v[172:173], v[96:97], v[172:173], v[100:101]
	v_pk_fma_f32 v[116:117], v[118:119], v[178:179], v[116:117] op_sel_hi:[1,0,1]
	v_pk_mul_f32 v[96:97], v[114:115], v[124:125] op_sel_hi:[1,0]
	v_pk_fma_f32 v[170:171], v[122:123], v[170:171], v[116:117]
	v_pk_fma_f32 v[96:97], v[102:103], v[178:179], v[96:97] op_sel_hi:[1,0,1]
	s_nop 0
	v_pk_fma_f32 v[174:175], v[98:99], v[174:175], v[96:97]
	v_pk_mul_f32 v[96:97], v[106:107], v[170:171]
	s_nop 0
	v_pk_fma_f32 v[96:97], v[104:105], v[168:169], v[96:97]
	s_nop 0
	v_pk_fma_f32 v[96:97], v[108:109], v[172:173], v[96:97]
	s_nop 0
	v_pk_fma_f32 v[96:97], v[110:111], v[174:175], v[96:97]
	s_nop 0
	v_add_f32_e32 v96, v96, v97
	s_nop 1
	v_add_f32_dpp v96, v96, v96 quad_perm:[1,0,3,2] row_mask:0xf bank_mask:0xf bound_ctrl:1
	s_nop 1
	v_add_f32_dpp v96, v96, v96 quad_perm:[2,3,0,1] row_mask:0xf bank_mask:0xf bound_ctrl:1
	s_nop 1
	v_mov_b32_dpp v97, v96 row_half_mirror row_mask:0xf bank_mask:0xf bound_ctrl:1
	s_and_saveexec_b64 s[46:47], s[42:43]
	v_add_f32_e32 v96, v96, v97
	ds_write_b32 v147, v96 offset:49152
	s_or_b64 exec, exec, s[46:47]
	s_add_i32 s54, s54, -2
	s_and_b64 vcc, exec, s[44:45]
	s_cbranch_vccnz .LBB0_1216
	s_mov_b32 s46, s72
	s_branch .LBB0_1208
